# v112: v106 with write-through (sc1) stores for the bf16 rows written by the folded epilogues (read by the next GEMM of the same XCD)
# baseline (speedup 1.0000x reference)
.Lrf_bar:
	s_barrier
	global_load_dwordx4 v[200:203], v253, s[10:11] offset:0
	global_load_dwordx4 v[204:207], v253, s[10:11] offset:256
	global_load_dwordx4 v[208:211], v253, s[10:11] offset:512
	global_load_dwordx4 v[212:215], v253, s[10:11] offset:768
	global_load_dwordx4 v[216:219], v253, s[10:11] offset:2048
	global_load_dwordx4 v[220:223], v253, s[10:11] offset:2304
	global_load_dwordx4 v[240:243], v253, s[10:11] offset:2560
	global_load_dwordx4 v[244:247], v253, s[10:11] offset:2816
	v_lshl_add_u32 v251, v236, 2, s68
	v_lshlrev_b32_e32 v251, 1, v251
	v_add_u32_e32 v249, s67, v235
	v_mul_u32_u24_e32 v249, 0x210, v249
	v_add_u32_e32 v251, v251, v249
	v_add_u32_e32 v252, 0x10800, v251
	s_mov_b32 s2, 0x3a800000
	s_waitcnt vmcnt(7)
	v_add_f32_e32 v200, v200, v201
	v_add_f32_e32 v202, v202, v203
	v_add_f32_e32 v200, v200, v202
	v_fma_f32 v200, v200, s2, v167
	v_rsq_f32_e32 v200, v200
	s_waitcnt vmcnt(6)
	v_add_f32_e32 v204, v204, v205
	v_add_f32_e32 v206, v206, v207
	v_add_f32_e32 v204, v204, v206
	v_fma_f32 v204, v204, s2, v167
	v_rsq_f32_e32 v204, v204
	s_waitcnt vmcnt(5)
	v_add_f32_e32 v208, v208, v209
	v_add_f32_e32 v210, v210, v211
	v_add_f32_e32 v208, v208, v210
	v_fma_f32 v208, v208, s2, v167
	v_rsq_f32_e32 v208, v208
	s_waitcnt vmcnt(4)
	v_add_f32_e32 v212, v212, v213
	v_add_f32_e32 v214, v214, v215
	v_add_f32_e32 v212, v212, v214
	v_fma_f32 v212, v212, s2, v167
	v_rsq_f32_e32 v212, v212
	s_waitcnt vmcnt(3)
	v_add_f32_e32 v216, v216, v217
	v_add_f32_e32 v218, v218, v219
	v_add_f32_e32 v216, v216, v218
	v_fma_f32 v216, v216, s2, v167
	v_rsq_f32_e32 v216, v216
	s_waitcnt vmcnt(2)
	v_add_f32_e32 v220, v220, v221
	v_add_f32_e32 v222, v222, v223
	v_add_f32_e32 v220, v220, v222
	v_fma_f32 v220, v220, s2, v167
	v_rsq_f32_e32 v220, v220
	s_waitcnt vmcnt(1)
	v_add_f32_e32 v240, v240, v241
	v_add_f32_e32 v242, v242, v243
	v_add_f32_e32 v240, v240, v242
	v_fma_f32 v240, v240, s2, v167
	v_rsq_f32_e32 v240, v240
	s_waitcnt vmcnt(0)
	v_add_f32_e32 v244, v244, v245
	v_add_f32_e32 v246, v246, v247
	v_add_f32_e32 v244, v244, v246
	v_fma_f32 v244, v244, s2, v167
	v_rsq_f32_e32 v244, v244
	s_nop 0
	v_readlane_b32 s8, v254, 61
	s_cmp_eq_u32 s8, 34
	s_cbranch_scc1 .Lrf_fin2
	global_store_dwordx4 v248, v[126:129], s[100:101] offset:0 sc1
	global_store_dwordx4 v248, v[122:125], s[100:101] offset:64 sc1
	global_store_dwordx4 v248, v[118:121], s[100:101] offset:512 sc1
	global_store_dwordx4 v248, v[114:117], s[100:101] offset:576 sc1
	s_nop 1
	v_mul_f32_e32 v126, v126, v200
	v_mul_f32_e32 v127, v127, v200
	v_mul_f32_e32 v128, v128, v200
	v_mul_f32_e32 v129, v129, v200
	v_fma_f32 v126, v126, v146, v162
	v_fma_f32 v127, v127, v147, v163
	v_fma_f32 v128, v128, v148, v164
	v_fma_f32 v129, v129, v149, v165
	v_cvt_pk_bf16_f32 v126, v126, v127
	v_cvt_pk_bf16_f32 v127, v128, v129
	v_mul_f32_e32 v122, v122, v200
	v_mul_f32_e32 v123, v123, v200
	v_mul_f32_e32 v124, v124, v200
	v_mul_f32_e32 v125, v125, v200
	v_fma_f32 v122, v122, v150, v188
	v_fma_f32 v123, v123, v151, v189
	v_fma_f32 v124, v124, v152, v190
	v_fma_f32 v125, v125, v153, v191
	v_cvt_pk_bf16_f32 v122, v122, v123
	v_cvt_pk_bf16_f32 v123, v124, v125
	v_mul_f32_e32 v118, v118, v200
	v_mul_f32_e32 v119, v119, v200
	v_mul_f32_e32 v120, v120, v200
	v_mul_f32_e32 v121, v121, v200
	v_fma_f32 v118, v118, v154, v192
	v_fma_f32 v119, v119, v155, v193
	v_fma_f32 v120, v120, v156, v194
	v_fma_f32 v121, v121, v157, v195
	v_cvt_pk_bf16_f32 v118, v118, v119
	v_cvt_pk_bf16_f32 v119, v120, v121
	v_mul_f32_e32 v114, v114, v200
	v_mul_f32_e32 v115, v115, v200
	v_mul_f32_e32 v116, v116, v200
	v_mul_f32_e32 v117, v117, v200
	v_fma_f32 v114, v114, v158, v196
	v_fma_f32 v115, v115, v159, v197
	v_fma_f32 v116, v116, v160, v198
	v_fma_f32 v117, v117, v161, v199
	v_cvt_pk_bf16_f32 v114, v114, v115
	v_cvt_pk_bf16_f32 v115, v116, v117
	ds_write_b64 v251, v[126:127] offset:0
	ds_write_b64 v251, v[122:123] offset:32
	ds_write_b64 v251, v[118:119] offset:256
	ds_write_b64 v251, v[114:115] offset:288
	s_add_u32 s8, s100, 0x10000
	s_addc_u32 s9, s101, 0
	global_store_dwordx4 v248, v[110:113], s[8:9] offset:0 sc1
	global_store_dwordx4 v248, v[106:109], s[8:9] offset:64 sc1
	global_store_dwordx4 v248, v[102:105], s[8:9] offset:512 sc1
	global_store_dwordx4 v248, v[98:101], s[8:9] offset:576 sc1
	s_nop 1
	v_mul_f32_e32 v110, v110, v204
	v_mul_f32_e32 v111, v111, v204
	v_mul_f32_e32 v112, v112, v204
	v_mul_f32_e32 v113, v113, v204
	v_fma_f32 v110, v110, v146, v162
	v_fma_f32 v111, v111, v147, v163
	v_fma_f32 v112, v112, v148, v164
	v_fma_f32 v113, v113, v149, v165
	v_cvt_pk_bf16_f32 v110, v110, v111
	v_cvt_pk_bf16_f32 v111, v112, v113
	v_mul_f32_e32 v106, v106, v204
	v_mul_f32_e32 v107, v107, v204
	v_mul_f32_e32 v108, v108, v204
	v_mul_f32_e32 v109, v109, v204
	v_fma_f32 v106, v106, v150, v188
	v_fma_f32 v107, v107, v151, v189
	v_fma_f32 v108, v108, v152, v190
	v_fma_f32 v109, v109, v153, v191
	v_cvt_pk_bf16_f32 v106, v106, v107
	v_cvt_pk_bf16_f32 v107, v108, v109
	v_mul_f32_e32 v102, v102, v204
	v_mul_f32_e32 v103, v103, v204
	v_mul_f32_e32 v104, v104, v204
	v_mul_f32_e32 v105, v105, v204
	v_fma_f32 v102, v102, v154, v192
	v_fma_f32 v103, v103, v155, v193
	v_fma_f32 v104, v104, v156, v194
	v_fma_f32 v105, v105, v157, v195
	v_cvt_pk_bf16_f32 v102, v102, v103
	v_cvt_pk_bf16_f32 v103, v104, v105
	v_mul_f32_e32 v98, v98, v204
	v_mul_f32_e32 v99, v99, v204
	v_mul_f32_e32 v100, v100, v204
	v_mul_f32_e32 v101, v101, v204
	v_fma_f32 v98, v98, v158, v196
	v_fma_f32 v99, v99, v159, v197
	v_fma_f32 v100, v100, v160, v198
	v_fma_f32 v101, v101, v161, v199
	v_cvt_pk_bf16_f32 v98, v98, v99
	v_cvt_pk_bf16_f32 v99, v100, v101
	ds_write_b64 v251, v[110:111] offset:8448
	ds_write_b64 v251, v[106:107] offset:8480
	ds_write_b64 v251, v[102:103] offset:8704
	ds_write_b64 v251, v[98:99] offset:8736
	s_add_u32 s8, s100, 0x20000
	s_addc_u32 s9, s101, 0
	global_store_dwordx4 v248, v[94:97], s[8:9] offset:0 sc1
	global_store_dwordx4 v248, v[90:93], s[8:9] offset:64 sc1
	global_store_dwordx4 v248, v[86:89], s[8:9] offset:512 sc1
	global_store_dwordx4 v248, v[82:85], s[8:9] offset:576 sc1
	s_nop 1
	v_mul_f32_e32 v94, v94, v208
	v_mul_f32_e32 v95, v95, v208
	v_mul_f32_e32 v96, v96, v208
	v_mul_f32_e32 v97, v97, v208
	v_fma_f32 v94, v94, v146, v162
	v_fma_f32 v95, v95, v147, v163
	v_fma_f32 v96, v96, v148, v164
	v_fma_f32 v97, v97, v149, v165
	v_cvt_pk_bf16_f32 v94, v94, v95
	v_cvt_pk_bf16_f32 v95, v96, v97
	v_mul_f32_e32 v90, v90, v208
	v_mul_f32_e32 v91, v91, v208
	v_mul_f32_e32 v92, v92, v208
	v_mul_f32_e32 v93, v93, v208
	v_fma_f32 v90, v90, v150, v188
	v_fma_f32 v91, v91, v151, v189
	v_fma_f32 v92, v92, v152, v190
	v_fma_f32 v93, v93, v153, v191
	v_cvt_pk_bf16_f32 v90, v90, v91
	v_cvt_pk_bf16_f32 v91, v92, v93
	v_mul_f32_e32 v86, v86, v208
	v_mul_f32_e32 v87, v87, v208
	v_mul_f32_e32 v88, v88, v208
	v_mul_f32_e32 v89, v89, v208
	v_fma_f32 v86, v86, v154, v192
	v_fma_f32 v87, v87, v155, v193
	v_fma_f32 v88, v88, v156, v194
	v_fma_f32 v89, v89, v157, v195
	v_cvt_pk_bf16_f32 v86, v86, v87
	v_cvt_pk_bf16_f32 v87, v88, v89
	v_mul_f32_e32 v82, v82, v208
	v_mul_f32_e32 v83, v83, v208
	v_mul_f32_e32 v84, v84, v208
	v_mul_f32_e32 v85, v85, v208
	v_fma_f32 v82, v82, v158, v196
	v_fma_f32 v83, v83, v159, v197
	v_fma_f32 v84, v84, v160, v198
	v_fma_f32 v85, v85, v161, v199
	v_cvt_pk_bf16_f32 v82, v82, v83
	v_cvt_pk_bf16_f32 v83, v84, v85
	ds_write_b64 v251, v[94:95] offset:16896
	ds_write_b64 v251, v[90:91] offset:16928
	ds_write_b64 v251, v[86:87] offset:17152
	ds_write_b64 v251, v[82:83] offset:17184
	s_add_u32 s8, s100, 0x30000
	s_addc_u32 s9, s101, 0
	global_store_dwordx4 v248, v[78:81], s[8:9] offset:0 sc1
	global_store_dwordx4 v248, v[74:77], s[8:9] offset:64 sc1
	global_store_dwordx4 v248, v[70:73], s[8:9] offset:512 sc1
	global_store_dwordx4 v248, v[66:69], s[8:9] offset:576 sc1
	s_nop 1
	v_mul_f32_e32 v78, v78, v212
	v_mul_f32_e32 v79, v79, v212
	v_mul_f32_e32 v80, v80, v212
	v_mul_f32_e32 v81, v81, v212
	v_fma_f32 v78, v78, v146, v162
	v_fma_f32 v79, v79, v147, v163
	v_fma_f32 v80, v80, v148, v164
	v_fma_f32 v81, v81, v149, v165
	v_cvt_pk_bf16_f32 v78, v78, v79
	v_cvt_pk_bf16_f32 v79, v80, v81
	v_mul_f32_e32 v74, v74, v212
	v_mul_f32_e32 v75, v75, v212
	v_mul_f32_e32 v76, v76, v212
	v_mul_f32_e32 v77, v77, v212
	v_fma_f32 v74, v74, v150, v188
	v_fma_f32 v75, v75, v151, v189
	v_fma_f32 v76, v76, v152, v190
	v_fma_f32 v77, v77, v153, v191
	v_cvt_pk_bf16_f32 v74, v74, v75
	v_cvt_pk_bf16_f32 v75, v76, v77
	v_mul_f32_e32 v70, v70, v212
	v_mul_f32_e32 v71, v71, v212
	v_mul_f32_e32 v72, v72, v212
	v_mul_f32_e32 v73, v73, v212
	v_fma_f32 v70, v70, v154, v192
	v_fma_f32 v71, v71, v155, v193
	v_fma_f32 v72, v72, v156, v194
	v_fma_f32 v73, v73, v157, v195
	v_cvt_pk_bf16_f32 v70, v70, v71
	v_cvt_pk_bf16_f32 v71, v72, v73
	v_mul_f32_e32 v66, v66, v212
	v_mul_f32_e32 v67, v67, v212
	v_mul_f32_e32 v68, v68, v212
	v_mul_f32_e32 v69, v69, v212
	v_fma_f32 v66, v66, v158, v196
	v_fma_f32 v67, v67, v159, v197
	v_fma_f32 v68, v68, v160, v198
	v_fma_f32 v69, v69, v161, v199
	v_cvt_pk_bf16_f32 v66, v66, v67
	v_cvt_pk_bf16_f32 v67, v68, v69
	ds_write_b64 v251, v[78:79] offset:25344
	ds_write_b64 v251, v[74:75] offset:25376
	ds_write_b64 v251, v[70:71] offset:25600
	ds_write_b64 v251, v[66:67] offset:25632
	s_add_u32 s8, s100, 0x80000
	s_addc_u32 s9, s101, 0
	global_store_dwordx4 v248, v[62:65], s[8:9] offset:0 sc1
	global_store_dwordx4 v248, v[58:61], s[8:9] offset:64 sc1
	global_store_dwordx4 v248, v[54:57], s[8:9] offset:512 sc1
	global_store_dwordx4 v248, v[50:53], s[8:9] offset:576 sc1
	s_nop 1
	v_mul_f32_e32 v62, v62, v216
	v_mul_f32_e32 v63, v63, v216
	v_mul_f32_e32 v64, v64, v216
	v_mul_f32_e32 v65, v65, v216
	v_fma_f32 v62, v62, v146, v162
	v_fma_f32 v63, v63, v147, v163
	v_fma_f32 v64, v64, v148, v164
	v_fma_f32 v65, v65, v149, v165
	v_cvt_pk_bf16_f32 v62, v62, v63
	v_cvt_pk_bf16_f32 v63, v64, v65
	v_mul_f32_e32 v58, v58, v216
	v_mul_f32_e32 v59, v59, v216
	v_mul_f32_e32 v60, v60, v216
	v_mul_f32_e32 v61, v61, v216
	v_fma_f32 v58, v58, v150, v188
	v_fma_f32 v59, v59, v151, v189
	v_fma_f32 v60, v60, v152, v190
	v_fma_f32 v61, v61, v153, v191
	v_cvt_pk_bf16_f32 v58, v58, v59
	v_cvt_pk_bf16_f32 v59, v60, v61
	v_mul_f32_e32 v54, v54, v216
	v_mul_f32_e32 v55, v55, v216
	v_mul_f32_e32 v56, v56, v216
	v_mul_f32_e32 v57, v57, v216
	v_fma_f32 v54, v54, v154, v192
	v_fma_f32 v55, v55, v155, v193
	v_fma_f32 v56, v56, v156, v194
	v_fma_f32 v57, v57, v157, v195
	v_cvt_pk_bf16_f32 v54, v54, v55
	v_cvt_pk_bf16_f32 v55, v56, v57
	v_mul_f32_e32 v50, v50, v216
	v_mul_f32_e32 v51, v51, v216
	v_mul_f32_e32 v52, v52, v216
	v_mul_f32_e32 v53, v53, v216
	v_fma_f32 v50, v50, v158, v196
	v_fma_f32 v51, v51, v159, v197
	v_fma_f32 v52, v52, v160, v198
	v_fma_f32 v53, v53, v161, v199
	v_cvt_pk_bf16_f32 v50, v50, v51
	v_cvt_pk_bf16_f32 v51, v52, v53
	ds_write_b64 v252, v[62:63] offset:0
	ds_write_b64 v252, v[58:59] offset:32
	ds_write_b64 v252, v[54:55] offset:256
	ds_write_b64 v252, v[50:51] offset:288
	s_add_u32 s8, s100, 0x90000
	s_addc_u32 s9, s101, 0
	global_store_dwordx4 v248, v[46:49], s[8:9] offset:0 sc1
	global_store_dwordx4 v248, v[42:45], s[8:9] offset:64 sc1
	global_store_dwordx4 v248, v[38:41], s[8:9] offset:512 sc1
	global_store_dwordx4 v248, v[34:37], s[8:9] offset:576 sc1
	s_nop 1
	v_mul_f32_e32 v46, v46, v220
	v_mul_f32_e32 v47, v47, v220
	v_mul_f32_e32 v48, v48, v220
	v_mul_f32_e32 v49, v49, v220
	v_fma_f32 v46, v46, v146, v162
	v_fma_f32 v47, v47, v147, v163
	v_fma_f32 v48, v48, v148, v164
	v_fma_f32 v49, v49, v149, v165
	v_cvt_pk_bf16_f32 v46, v46, v47
	v_cvt_pk_bf16_f32 v47, v48, v49
	v_mul_f32_e32 v42, v42, v220
	v_mul_f32_e32 v43, v43, v220
	v_mul_f32_e32 v44, v44, v220
	v_mul_f32_e32 v45, v45, v220
	v_fma_f32 v42, v42, v150, v188
	v_fma_f32 v43, v43, v151, v189
	v_fma_f32 v44, v44, v152, v190
	v_fma_f32 v45, v45, v153, v191
	v_cvt_pk_bf16_f32 v42, v42, v43
	v_cvt_pk_bf16_f32 v43, v44, v45
	v_mul_f32_e32 v38, v38, v220
	v_mul_f32_e32 v39, v39, v220
	v_mul_f32_e32 v40, v40, v220
	v_mul_f32_e32 v41, v41, v220
	v_fma_f32 v38, v38, v154, v192
	v_fma_f32 v39, v39, v155, v193
	v_fma_f32 v40, v40, v156, v194
	v_fma_f32 v41, v41, v157, v195
	v_cvt_pk_bf16_f32 v38, v38, v39
	v_cvt_pk_bf16_f32 v39, v40, v41
	v_mul_f32_e32 v34, v34, v220
	v_mul_f32_e32 v35, v35, v220
	v_mul_f32_e32 v36, v36, v220
	v_mul_f32_e32 v37, v37, v220
	v_fma_f32 v34, v34, v158, v196
	v_fma_f32 v35, v35, v159, v197
	v_fma_f32 v36, v36, v160, v198
	v_fma_f32 v37, v37, v161, v199
	v_cvt_pk_bf16_f32 v34, v34, v35
	v_cvt_pk_bf16_f32 v35, v36, v37
	ds_write_b64 v252, v[46:47] offset:8448
	ds_write_b64 v252, v[42:43] offset:8480
	ds_write_b64 v252, v[38:39] offset:8704
	ds_write_b64 v252, v[34:35] offset:8736
	s_add_u32 s8, s100, 0xa0000
	s_addc_u32 s9, s101, 0
	global_store_dwordx4 v248, v[30:33], s[8:9] offset:0 sc1
	global_store_dwordx4 v248, v[26:29], s[8:9] offset:64 sc1
	global_store_dwordx4 v248, v[22:25], s[8:9] offset:512 sc1
	global_store_dwordx4 v248, v[18:21], s[8:9] offset:576 sc1
	s_nop 1
	v_mul_f32_e32 v30, v30, v240
	v_mul_f32_e32 v31, v31, v240
	v_mul_f32_e32 v32, v32, v240
	v_mul_f32_e32 v33, v33, v240
	v_fma_f32 v30, v30, v146, v162
	v_fma_f32 v31, v31, v147, v163
	v_fma_f32 v32, v32, v148, v164
	v_fma_f32 v33, v33, v149, v165
	v_cvt_pk_bf16_f32 v30, v30, v31
	v_cvt_pk_bf16_f32 v31, v32, v33
	v_mul_f32_e32 v26, v26, v240
	v_mul_f32_e32 v27, v27, v240
	v_mul_f32_e32 v28, v28, v240
	v_mul_f32_e32 v29, v29, v240
	v_fma_f32 v26, v26, v150, v188
	v_fma_f32 v27, v27, v151, v189
	v_fma_f32 v28, v28, v152, v190
	v_fma_f32 v29, v29, v153, v191
	v_cvt_pk_bf16_f32 v26, v26, v27
	v_cvt_pk_bf16_f32 v27, v28, v29
	v_mul_f32_e32 v22, v22, v240
	v_mul_f32_e32 v23, v23, v240
	v_mul_f32_e32 v24, v24, v240
	v_mul_f32_e32 v25, v25, v240
	v_fma_f32 v22, v22, v154, v192
	v_fma_f32 v23, v23, v155, v193
	v_fma_f32 v24, v24, v156, v194
	v_fma_f32 v25, v25, v157, v195
	v_cvt_pk_bf16_f32 v22, v22, v23
	v_cvt_pk_bf16_f32 v23, v24, v25
	v_mul_f32_e32 v18, v18, v240
	v_mul_f32_e32 v19, v19, v240
	v_mul_f32_e32 v20, v20, v240
	v_mul_f32_e32 v21, v21, v240
	v_fma_f32 v18, v18, v158, v196
	v_fma_f32 v19, v19, v159, v197
	v_fma_f32 v20, v20, v160, v198
	v_fma_f32 v21, v21, v161, v199
	v_cvt_pk_bf16_f32 v18, v18, v19
	v_cvt_pk_bf16_f32 v19, v20, v21
	ds_write_b64 v252, v[30:31] offset:16896
	ds_write_b64 v252, v[26:27] offset:16928
	ds_write_b64 v252, v[22:23] offset:17152
	ds_write_b64 v252, v[18:19] offset:17184
	s_add_u32 s8, s100, 0xb0000
	s_addc_u32 s9, s101, 0
	global_store_dwordx4 v248, v[14:17], s[8:9] offset:0 sc1
	global_store_dwordx4 v248, v[10:13], s[8:9] offset:64 sc1
	global_store_dwordx4 v248, v[6:9], s[8:9] offset:512 sc1
	global_store_dwordx4 v248, v[2:5], s[8:9] offset:576 sc1
	s_nop 1
	v_mul_f32_e32 v14, v14, v244
	v_mul_f32_e32 v15, v15, v244
	v_mul_f32_e32 v16, v16, v244
	v_mul_f32_e32 v17, v17, v244
	v_fma_f32 v14, v14, v146, v162
	v_fma_f32 v15, v15, v147, v163
	v_fma_f32 v16, v16, v148, v164
	v_fma_f32 v17, v17, v149, v165
	v_cvt_pk_bf16_f32 v14, v14, v15
	v_cvt_pk_bf16_f32 v15, v16, v17
	v_mul_f32_e32 v10, v10, v244
	v_mul_f32_e32 v11, v11, v244
	v_mul_f32_e32 v12, v12, v244
	v_mul_f32_e32 v13, v13, v244
	v_fma_f32 v10, v10, v150, v188
	v_fma_f32 v11, v11, v151, v189
	v_fma_f32 v12, v12, v152, v190
	v_fma_f32 v13, v13, v153, v191
	v_cvt_pk_bf16_f32 v10, v10, v11
	v_cvt_pk_bf16_f32 v11, v12, v13
	v_mul_f32_e32 v6, v6, v244
	v_mul_f32_e32 v7, v7, v244
	v_mul_f32_e32 v8, v8, v244
	v_mul_f32_e32 v9, v9, v244
	v_fma_f32 v6, v6, v154, v192
	v_fma_f32 v7, v7, v155, v193
	v_fma_f32 v8, v8, v156, v194
	v_fma_f32 v9, v9, v157, v195
	v_cvt_pk_bf16_f32 v6, v6, v7
	v_cvt_pk_bf16_f32 v7, v8, v9
	v_mul_f32_e32 v2, v2, v244
	v_mul_f32_e32 v3, v3, v244
	v_mul_f32_e32 v4, v4, v244
	v_mul_f32_e32 v5, v5, v244
	v_fma_f32 v2, v2, v158, v196
	v_fma_f32 v3, v3, v159, v197
	v_fma_f32 v4, v4, v160, v198
	v_fma_f32 v5, v5, v161, v199
	v_cvt_pk_bf16_f32 v2, v2, v3
	v_cvt_pk_bf16_f32 v3, v4, v5
	ds_write_b64 v252, v[14:15] offset:25344
	ds_write_b64 v252, v[10:11] offset:25376
	ds_write_b64 v252, v[6:7] offset:25600
	ds_write_b64 v252, v[2:3] offset:25632
	v_lshl_add_u32 v249, v236, 4, v235
	v_lshrrev_b32_e32 v250, 5, v249
	v_and_b32_e32 v249, 31, v249
	v_lshlrev_b32_e32 v249, 4, v249
	v_lshl_add_u32 v250, s3, 5, v250
	v_mul_u32_u24_e32 v251, 0x210, v250
	v_add_u32_e32 v251, v251, v249
	v_lshl_add_u32 v248, v250, 11, v249
	v_readlane_b32 s12, v255, 9
	v_readlane_b32 s13, v255, 10
	s_lshl_b32 s2, s17, 19
	s_lshl_b32 s8, s48, 9
	s_add_i32 s2, s2, s8
	s_add_u32 s12, s12, s2
	s_addc_u32 s13, s13, 0
	s_waitcnt lgkmcnt(0)
	s_barrier
	ds_read_b128 v[2:5], v251 offset:0
	ds_read_b128 v[6:9], v251 offset:1056
	ds_read_b128 v[10:13], v251 offset:2112
	ds_read_b128 v[14:17], v251 offset:3168
	ds_read_b128 v[18:21], v251 offset:4224
	ds_read_b128 v[22:25], v251 offset:5280
	ds_read_b128 v[26:29], v251 offset:6336
	ds_read_b128 v[30:33], v251 offset:7392
	ds_read_b128 v[34:37], v251 offset:8448
	ds_read_b128 v[38:41], v251 offset:9504
	ds_read_b128 v[42:45], v251 offset:10560
	ds_read_b128 v[46:49], v251 offset:11616
	ds_read_b128 v[50:53], v251 offset:12672
	ds_read_b128 v[54:57], v251 offset:13728
	ds_read_b128 v[58:61], v251 offset:14784
	ds_read_b128 v[62:65], v251 offset:15840
	s_waitcnt lgkmcnt(15)
	global_store_dwordx4 v248, v[2:5], s[12:13] sc1
	s_waitcnt lgkmcnt(14)
	s_add_u32 s14, s12, 0x1000
	s_addc_u32 s15, s13, 0
	global_store_dwordx4 v248, v[6:9], s[14:15] sc1
	s_waitcnt lgkmcnt(13)
	s_add_u32 s14, s12, 0x2000
	s_addc_u32 s15, s13, 0
	global_store_dwordx4 v248, v[10:13], s[14:15] sc1
	s_waitcnt lgkmcnt(12)
	s_add_u32 s14, s12, 0x3000
	s_addc_u32 s15, s13, 0
	global_store_dwordx4 v248, v[14:17], s[14:15] sc1
	s_waitcnt lgkmcnt(11)
	s_add_u32 s14, s12, 0x4000
	s_addc_u32 s15, s13, 0
	global_store_dwordx4 v248, v[18:21], s[14:15] sc1
	s_waitcnt lgkmcnt(10)
	s_add_u32 s14, s12, 0x5000
	s_addc_u32 s15, s13, 0
	global_store_dwordx4 v248, v[22:25], s[14:15] sc1
	s_waitcnt lgkmcnt(9)
	s_add_u32 s14, s12, 0x6000
	s_addc_u32 s15, s13, 0
	global_store_dwordx4 v248, v[26:29], s[14:15] sc1
	s_waitcnt lgkmcnt(8)
	s_add_u32 s14, s12, 0x7000
	s_addc_u32 s15, s13, 0
	global_store_dwordx4 v248, v[30:33], s[14:15] sc1
	s_waitcnt lgkmcnt(7)
	s_add_u32 s14, s12, 0x8000
	s_addc_u32 s15, s13, 0
	global_store_dwordx4 v248, v[34:37], s[14:15] sc1
	s_waitcnt lgkmcnt(6)
	s_add_u32 s14, s12, 0x9000
	s_addc_u32 s15, s13, 0
	global_store_dwordx4 v248, v[38:41], s[14:15] sc1
	s_waitcnt lgkmcnt(5)
	s_add_u32 s14, s12, 0xa000
	s_addc_u32 s15, s13, 0
	global_store_dwordx4 v248, v[42:45], s[14:15] sc1
	s_waitcnt lgkmcnt(4)
	s_add_u32 s14, s12, 0xb000
	s_addc_u32 s15, s13, 0
	global_store_dwordx4 v248, v[46:49], s[14:15] sc1
	s_waitcnt lgkmcnt(3)
	s_add_u32 s14, s12, 0xc000
	s_addc_u32 s15, s13, 0
	global_store_dwordx4 v248, v[50:53], s[14:15] sc1
	s_waitcnt lgkmcnt(2)
	s_add_u32 s14, s12, 0xd000
	s_addc_u32 s15, s13, 0
	global_store_dwordx4 v248, v[54:57], s[14:15] sc1
	s_waitcnt lgkmcnt(1)
	s_add_u32 s14, s12, 0xe000
	s_addc_u32 s15, s13, 0
	global_store_dwordx4 v248, v[58:61], s[14:15] sc1
	s_waitcnt lgkmcnt(0)
	s_add_u32 s14, s12, 0xf000
	s_addc_u32 s15, s13, 0
	global_store_dwordx4 v248, v[62:65], s[14:15] sc1
	s_branch .LBB0_561
